# v105 + blocked row assignment in the P15 row pass
# baseline (speedup 1.0000x reference)
.LBB0_1602:
	s_cmp_lt_i32 s72, 16
	s_cselect_b64 s[2:3], -1, 0
	s_and_b64 s[0:1], s[2:3], s[0:1]
	s_andn2_b64 vcc, exec, s[0:1]
	s_cbranch_vccnz .LBB0_1608
	s_cmpk_gt_i32 s96, 0x21ff
	s_cbranch_scc1 .LBB0_1608
	v_readlane_b32 s0, v242, 12
	v_readlane_b32 s1, v242, 13
	v_readlane_b32 s6, v242, 51
	v_readlane_b32 s7, v242, 52
	v_lshlrev_b32_e32 v252, 3, v142
	v_lshlrev_b32_e32 v253, 4, v142
	v_add_u32_e32 v254, 0x1000, v253
	v_mov_b32_e32 v255, 0x358637bd
	v_xor_b32_e32 v128, 1, v142
	v_lshlrev_b32_e32 v244, 2, v128
	v_xor_b32_e32 v128, 2, v142
	v_lshlrev_b32_e32 v245, 2, v128
	v_xor_b32_e32 v128, 4, v142
	v_lshlrev_b32_e32 v246, 2, v128
	v_xor_b32_e32 v128, 8, v142
	v_lshlrev_b32_e32 v247, 2, v128
	v_xor_b32_e32 v128, 16, v142
	v_lshlrev_b32_e32 v248, 2, v128
	v_xor_b32_e32 v128, 32, v142
	v_lshlrev_b32_e32 v249, 2, v128
	s_add_u32 s0, s0, 0x2000
	s_addc_u32 s1, s1, 0
	global_load_dwordx4 v[0:3], v253, s[0:1] offset:0
	global_load_dwordx4 v[4:7], v253, s[0:1] offset:1024
	global_load_dwordx4 v[8:11], v253, s[0:1] offset:2048
	global_load_dwordx4 v[12:15], v253, s[0:1] offset:3072
	global_load_dwordx4 v[16:19], v254, s[0:1] offset:0
	global_load_dwordx4 v[20:23], v254, s[0:1] offset:1024
	global_load_dwordx4 v[24:27], v254, s[0:1] offset:2048
	global_load_dwordx4 v[28:31], v254, s[0:1] offset:3072
	s_lshr_b32 s8, s96, 3
	s_mul_i32 s8, s8, 34
	s_and_b32 s9, s96, 7
	s_add_u32 s8, s8, s9
	s_mov_b32 s9, 0
	s_and_b32 s11, s96, 7
	s_lshl_b64 s[4:5], s[8:9], 12
	s_add_u32 s0, s6, s4
	s_addc_u32 s1, s7, s5
	s_add_u32 s2, s40, s4
	s_addc_u32 s3, s41, s5
	global_load_dwordx2 v[32:33], v252, s[0:1] offset:0 nt
	global_load_dwordx2 v[34:35], v252, s[0:1] offset:512 nt
	global_load_dwordx2 v[36:37], v252, s[0:1] offset:1024 nt
	global_load_dwordx2 v[38:39], v252, s[0:1] offset:1536 nt
	global_load_dwordx2 v[40:41], v252, s[0:1] offset:2048 nt
	global_load_dwordx2 v[42:43], v252, s[0:1] offset:2560 nt
	global_load_dwordx2 v[44:45], v252, s[0:1] offset:3072 nt
	global_load_dwordx2 v[46:47], v252, s[0:1] offset:3584 nt
	global_load_dwordx2 v[48:49], v252, s[2:3] offset:0 nt
	global_load_dwordx2 v[50:51], v252, s[2:3] offset:512 nt
	global_load_dwordx2 v[52:53], v252, s[2:3] offset:1024 nt
	global_load_dwordx2 v[54:55], v252, s[2:3] offset:1536 nt
	global_load_dwordx2 v[56:57], v252, s[2:3] offset:2048 nt
	global_load_dwordx2 v[58:59], v252, s[2:3] offset:2560 nt
	global_load_dwordx2 v[60:61], v252, s[2:3] offset:3072 nt
	global_load_dwordx2 v[62:63], v252, s[2:3] offset:3584 nt
	s_add_u32 s0, s0, 0x8000
	s_addc_u32 s1, s1, 0
	s_add_u32 s2, s2, 0x8000
	s_addc_u32 s3, s3, 0
	global_load_dwordx2 v[64:65], v252, s[0:1] offset:0 nt
	global_load_dwordx2 v[66:67], v252, s[0:1] offset:512 nt
	global_load_dwordx2 v[68:69], v252, s[0:1] offset:1024 nt
	global_load_dwordx2 v[70:71], v252, s[0:1] offset:1536 nt
	global_load_dwordx2 v[72:73], v252, s[0:1] offset:2048 nt
	global_load_dwordx2 v[74:75], v252, s[0:1] offset:2560 nt
	global_load_dwordx2 v[76:77], v252, s[0:1] offset:3072 nt
	global_load_dwordx2 v[78:79], v252, s[0:1] offset:3584 nt
	global_load_dwordx2 v[80:81], v252, s[2:3] offset:0 nt
	global_load_dwordx2 v[82:83], v252, s[2:3] offset:512 nt
	global_load_dwordx2 v[84:85], v252, s[2:3] offset:1024 nt
	global_load_dwordx2 v[86:87], v252, s[2:3] offset:1536 nt
	global_load_dwordx2 v[88:89], v252, s[2:3] offset:2048 nt
	global_load_dwordx2 v[90:91], v252, s[2:3] offset:2560 nt
	global_load_dwordx2 v[92:93], v252, s[2:3] offset:3072 nt
	global_load_dwordx2 v[94:95], v252, s[2:3] offset:3584 nt
	s_add_u32 s0, s0, 0x8000
	s_addc_u32 s1, s1, 0
	s_add_u32 s2, s2, 0x8000
	s_addc_u32 s3, s3, 0
	global_load_dwordx2 v[96:97], v252, s[0:1] offset:0 nt
	global_load_dwordx2 v[98:99], v252, s[0:1] offset:512 nt
	global_load_dwordx2 v[100:101], v252, s[0:1] offset:1024 nt
	global_load_dwordx2 v[102:103], v252, s[0:1] offset:1536 nt
	global_load_dwordx2 v[104:105], v252, s[0:1] offset:2048 nt
	global_load_dwordx2 v[106:107], v252, s[0:1] offset:2560 nt
	global_load_dwordx2 v[108:109], v252, s[0:1] offset:3072 nt
	global_load_dwordx2 v[110:111], v252, s[0:1] offset:3584 nt
	global_load_dwordx2 v[112:113], v252, s[2:3] offset:0 nt
	global_load_dwordx2 v[114:115], v252, s[2:3] offset:512 nt
	global_load_dwordx2 v[116:117], v252, s[2:3] offset:1024 nt
	global_load_dwordx2 v[118:119], v252, s[2:3] offset:1536 nt
	global_load_dwordx2 v[120:121], v252, s[2:3] offset:2048 nt
	global_load_dwordx2 v[122:123], v252, s[2:3] offset:2560 nt
	global_load_dwordx2 v[124:125], v252, s[2:3] offset:3072 nt
	global_load_dwordx2 v[126:127], v252, s[2:3] offset:3584 nt
	s_add_u32 s0, s0, 0x8000
	s_addc_u32 s1, s1, 0
	s_add_u32 s2, s2, 0x8000
	s_addc_u32 s3, s3, 0
	s_lshl_b64 s[4:5], s[8:9], 13
	s_add_u32 s4, s68, s4
	s_addc_u32 s5, s69, s5
	v_mov_b32_e32 v250, v253
	v_mov_b32_e32 v251, 0
	v_lshl_add_u64 v[250:251], s[4:5], 0, v[250:251]
	s_mov_b64 s[12:13], 0x10000
	s_mov_b64 s[14:15], 0x1000
	s_mov_b32 s10, 0x800000
	s_waitcnt vmcnt(32)
	v_lshlrev_b32_e32 v208, 16, v48
	v_and_b32_e32 v209, 0xffff0000, v48
	v_lshlrev_b32_e32 v210, 16, v49
	v_and_b32_e32 v211, 0xffff0000, v49
	v_lshlrev_b32_e32 v212, 16, v50
	v_and_b32_e32 v213, 0xffff0000, v50
	v_lshlrev_b32_e32 v214, 16, v51
	v_and_b32_e32 v215, 0xffff0000, v51
	v_lshlrev_b32_e32 v216, 16, v52
	v_and_b32_e32 v217, 0xffff0000, v52
	v_lshlrev_b32_e32 v218, 16, v53
	v_and_b32_e32 v219, 0xffff0000, v53
	v_lshlrev_b32_e32 v220, 16, v54
	v_and_b32_e32 v221, 0xffff0000, v54
	v_lshlrev_b32_e32 v222, 16, v55
	v_and_b32_e32 v223, 0xffff0000, v55
	v_lshlrev_b32_e32 v224, 16, v56
	v_and_b32_e32 v225, 0xffff0000, v56
	v_lshlrev_b32_e32 v226, 16, v57
	v_and_b32_e32 v227, 0xffff0000, v57
	v_lshlrev_b32_e32 v228, 16, v58
	v_and_b32_e32 v229, 0xffff0000, v58
	v_lshlrev_b32_e32 v230, 16, v59
	v_and_b32_e32 v231, 0xffff0000, v59
	v_lshlrev_b32_e32 v232, 16, v60
	v_and_b32_e32 v233, 0xffff0000, v60
	v_lshlrev_b32_e32 v234, 16, v61
	v_and_b32_e32 v235, 0xffff0000, v61
	v_lshlrev_b32_e32 v236, 16, v62
	v_and_b32_e32 v237, 0xffff0000, v62
	v_lshlrev_b32_e32 v238, 16, v63
	v_and_b32_e32 v239, 0xffff0000, v63
	v_mul_f32_e32 v128, v208, v208
	v_fmac_f32_e32 v128, v209, v209
	v_mul_f32_e32 v129, v210, v210
	v_fmac_f32_e32 v129, v211, v211
	v_add_f32_e32 v128, v128, v129
	v_mul_f32_e32 v129, v212, v212
	v_fmac_f32_e32 v129, v213, v213
	v_mul_f32_e32 v132, v214, v214
	v_fmac_f32_e32 v132, v215, v215
	v_add_f32_e32 v129, v129, v132
	v_add_f32_e32 v128, v128, v129
	v_mul_f32_e32 v129, v216, v216
	v_fmac_f32_e32 v129, v217, v217
	v_mul_f32_e32 v132, v218, v218
	v_fmac_f32_e32 v132, v219, v219
	v_add_f32_e32 v129, v129, v132
	v_add_f32_e32 v128, v128, v129
	v_mul_f32_e32 v129, v220, v220
	v_fmac_f32_e32 v129, v221, v221
	v_mul_f32_e32 v132, v222, v222
	v_fmac_f32_e32 v132, v223, v223
	v_add_f32_e32 v129, v129, v132
	v_add_f32_e32 v128, v128, v129
	v_mul_f32_e32 v129, v224, v224
	v_fmac_f32_e32 v129, v225, v225
	v_mul_f32_e32 v132, v226, v226
	v_fmac_f32_e32 v132, v227, v227
	v_add_f32_e32 v129, v129, v132
	v_add_f32_e32 v128, v128, v129
	v_mul_f32_e32 v129, v228, v228
	v_fmac_f32_e32 v129, v229, v229
	v_mul_f32_e32 v132, v230, v230
	v_fmac_f32_e32 v132, v231, v231
	v_add_f32_e32 v129, v129, v132
	v_add_f32_e32 v128, v128, v129
	v_mul_f32_e32 v129, v232, v232
	v_fmac_f32_e32 v129, v233, v233
	v_mul_f32_e32 v132, v234, v234
	v_fmac_f32_e32 v132, v235, v235
	v_add_f32_e32 v129, v129, v132
	v_add_f32_e32 v128, v128, v129
	v_mul_f32_e32 v129, v236, v236
	v_fmac_f32_e32 v129, v237, v237
	v_mul_f32_e32 v132, v238, v238
	v_fmac_f32_e32 v132, v239, v239
	v_add_f32_e32 v129, v129, v132
	v_add_f32_e32 v128, v128, v129
	ds_bpermute_b32 v129, v244, v128
	s_waitcnt lgkmcnt(0)
	v_add_f32_e32 v128, v128, v129
	ds_bpermute_b32 v129, v245, v128
	s_waitcnt lgkmcnt(0)
	v_add_f32_e32 v128, v128, v129
	ds_bpermute_b32 v129, v246, v128
	s_waitcnt lgkmcnt(0)
	v_add_f32_e32 v128, v128, v129
	ds_bpermute_b32 v129, v247, v128
	s_waitcnt lgkmcnt(0)
	v_add_f32_e32 v128, v128, v129
	ds_bpermute_b32 v129, v248, v128
	s_waitcnt lgkmcnt(0)
	v_add_f32_e32 v128, v128, v129
	ds_bpermute_b32 v129, v249, v128
	s_waitcnt lgkmcnt(0)
	v_add_f32_e32 v128, v128, v129
	v_fmamk_f32 v128, v128, 0x3a000000, v255
	v_mul_f32_e32 v129, 0x4b800000, v128
	v_cmp_gt_f32_e32 vcc, s10, v128
	s_nop 1
	v_cndmask_b32_e32 v128, v128, v129, vcc
	v_rsq_f32_e32 v128, v128
	s_nop 0
	v_mul_f32_e32 v129, 0x45800000, v128
	v_cndmask_b32_e32 v130, v128, v129, vcc
	v_lshl_add_u64 v[140:141], v[250:251], 0, s[14:15]
	v_lshlrev_b32_e32 v136, 16, v32
	v_and_b32_e32 v137, 0xffff0000, v32
	v_lshlrev_b32_e32 v138, 16, v33
	v_and_b32_e32 v139, 0xffff0000, v33
	v_pk_mul_f32 v[208:209], v[130:131], v[208:209] op_sel_hi:[0,1]
	v_pk_fma_f32 v[208:209], v[0:1], v[208:209], v[136:137]
	v_pk_mul_f32 v[210:211], v[130:131], v[210:211] op_sel_hi:[0,1]
	v_pk_fma_f32 v[210:211], v[2:3], v[210:211], v[138:139]
	global_store_dwordx4 v[250:251], v[208:211], off offset:0 nt
	v_lshlrev_b32_e32 v136, 16, v34
	v_and_b32_e32 v137, 0xffff0000, v34
	v_lshlrev_b32_e32 v138, 16, v35
	v_and_b32_e32 v139, 0xffff0000, v35
	v_pk_mul_f32 v[212:213], v[130:131], v[212:213] op_sel_hi:[0,1]
	v_pk_fma_f32 v[212:213], v[4:5], v[212:213], v[136:137]
	v_pk_mul_f32 v[214:215], v[130:131], v[214:215] op_sel_hi:[0,1]
	v_pk_fma_f32 v[214:215], v[6:7], v[214:215], v[138:139]
	global_store_dwordx4 v[250:251], v[212:215], off offset:1024 nt
	v_lshlrev_b32_e32 v136, 16, v36
	v_and_b32_e32 v137, 0xffff0000, v36
	v_lshlrev_b32_e32 v138, 16, v37
	v_and_b32_e32 v139, 0xffff0000, v37
	v_pk_mul_f32 v[216:217], v[130:131], v[216:217] op_sel_hi:[0,1]
	v_pk_fma_f32 v[216:217], v[8:9], v[216:217], v[136:137]
	v_pk_mul_f32 v[218:219], v[130:131], v[218:219] op_sel_hi:[0,1]
	v_pk_fma_f32 v[218:219], v[10:11], v[218:219], v[138:139]
	global_store_dwordx4 v[250:251], v[216:219], off offset:2048 nt
	v_lshlrev_b32_e32 v136, 16, v38
	v_and_b32_e32 v137, 0xffff0000, v38
	v_lshlrev_b32_e32 v138, 16, v39
	v_and_b32_e32 v139, 0xffff0000, v39
	v_pk_mul_f32 v[220:221], v[130:131], v[220:221] op_sel_hi:[0,1]
	v_pk_fma_f32 v[220:221], v[12:13], v[220:221], v[136:137]
	v_pk_mul_f32 v[222:223], v[130:131], v[222:223] op_sel_hi:[0,1]
	v_pk_fma_f32 v[222:223], v[14:15], v[222:223], v[138:139]
	global_store_dwordx4 v[250:251], v[220:223], off offset:3072 nt
	v_lshlrev_b32_e32 v136, 16, v40
	v_and_b32_e32 v137, 0xffff0000, v40
	v_lshlrev_b32_e32 v138, 16, v41
	v_and_b32_e32 v139, 0xffff0000, v41
	v_pk_mul_f32 v[224:225], v[130:131], v[224:225] op_sel_hi:[0,1]
	v_pk_fma_f32 v[224:225], v[16:17], v[224:225], v[136:137]
	v_pk_mul_f32 v[226:227], v[130:131], v[226:227] op_sel_hi:[0,1]
	v_pk_fma_f32 v[226:227], v[18:19], v[226:227], v[138:139]
	global_store_dwordx4 v[140:141], v[224:227], off offset:0 nt
	v_lshlrev_b32_e32 v136, 16, v42
	v_and_b32_e32 v137, 0xffff0000, v42
	v_lshlrev_b32_e32 v138, 16, v43
	v_and_b32_e32 v139, 0xffff0000, v43
	v_pk_mul_f32 v[228:229], v[130:131], v[228:229] op_sel_hi:[0,1]
	v_pk_fma_f32 v[228:229], v[20:21], v[228:229], v[136:137]
	v_pk_mul_f32 v[230:231], v[130:131], v[230:231] op_sel_hi:[0,1]
	v_pk_fma_f32 v[230:231], v[22:23], v[230:231], v[138:139]
	global_store_dwordx4 v[140:141], v[228:231], off offset:1024 nt
	v_lshlrev_b32_e32 v136, 16, v44
	v_and_b32_e32 v137, 0xffff0000, v44
	v_lshlrev_b32_e32 v138, 16, v45
	v_and_b32_e32 v139, 0xffff0000, v45
	v_pk_mul_f32 v[232:233], v[130:131], v[232:233] op_sel_hi:[0,1]
	v_pk_fma_f32 v[232:233], v[24:25], v[232:233], v[136:137]
	v_pk_mul_f32 v[234:235], v[130:131], v[234:235] op_sel_hi:[0,1]
	v_pk_fma_f32 v[234:235], v[26:27], v[234:235], v[138:139]
	global_store_dwordx4 v[140:141], v[232:235], off offset:2048 nt
	v_lshlrev_b32_e32 v136, 16, v46
	v_and_b32_e32 v137, 0xffff0000, v46
	v_lshlrev_b32_e32 v138, 16, v47
	v_and_b32_e32 v139, 0xffff0000, v47
	v_pk_mul_f32 v[236:237], v[130:131], v[236:237] op_sel_hi:[0,1]
	v_pk_fma_f32 v[236:237], v[28:29], v[236:237], v[136:137]
	v_pk_mul_f32 v[238:239], v[130:131], v[238:239] op_sel_hi:[0,1]
	v_pk_fma_f32 v[238:239], v[30:31], v[238:239], v[138:139]
	global_store_dwordx4 v[140:141], v[236:239], off offset:3072 nt
	v_lshl_add_u64 v[250:251], v[250:251], 0, s[12:13]
	global_load_dwordx2 v[144:145], v252, s[0:1] offset:0 nt
	global_load_dwordx2 v[146:147], v252, s[0:1] offset:512 nt
	global_load_dwordx2 v[148:149], v252, s[0:1] offset:1024 nt
	global_load_dwordx2 v[150:151], v252, s[0:1] offset:1536 nt
	global_load_dwordx2 v[152:153], v252, s[0:1] offset:2048 nt
	global_load_dwordx2 v[154:155], v252, s[0:1] offset:2560 nt
	global_load_dwordx2 v[156:157], v252, s[0:1] offset:3072 nt
	global_load_dwordx2 v[158:159], v252, s[0:1] offset:3584 nt
	global_load_dwordx2 v[160:161], v252, s[2:3] offset:0 nt
	global_load_dwordx2 v[162:163], v252, s[2:3] offset:512 nt
	global_load_dwordx2 v[164:165], v252, s[2:3] offset:1024 nt
	global_load_dwordx2 v[166:167], v252, s[2:3] offset:1536 nt
	global_load_dwordx2 v[168:169], v252, s[2:3] offset:2048 nt
	global_load_dwordx2 v[170:171], v252, s[2:3] offset:2560 nt
	global_load_dwordx2 v[172:173], v252, s[2:3] offset:3072 nt
	global_load_dwordx2 v[174:175], v252, s[2:3] offset:3584 nt
	s_add_u32 s0, s0, 0x8000
	s_addc_u32 s1, s1, 0
	s_add_u32 s2, s2, 0x8000
	s_addc_u32 s3, s3, 0
	s_waitcnt vmcnt(40)
	v_lshlrev_b32_e32 v208, 16, v80
	v_and_b32_e32 v209, 0xffff0000, v80
	v_lshlrev_b32_e32 v210, 16, v81
	v_and_b32_e32 v211, 0xffff0000, v81
	v_lshlrev_b32_e32 v212, 16, v82
	v_and_b32_e32 v213, 0xffff0000, v82
	v_lshlrev_b32_e32 v214, 16, v83
	v_and_b32_e32 v215, 0xffff0000, v83
	v_lshlrev_b32_e32 v216, 16, v84
	v_and_b32_e32 v217, 0xffff0000, v84
	v_lshlrev_b32_e32 v218, 16, v85
	v_and_b32_e32 v219, 0xffff0000, v85
	v_lshlrev_b32_e32 v220, 16, v86
	v_and_b32_e32 v221, 0xffff0000, v86
	v_lshlrev_b32_e32 v222, 16, v87
	v_and_b32_e32 v223, 0xffff0000, v87
	v_lshlrev_b32_e32 v224, 16, v88
	v_and_b32_e32 v225, 0xffff0000, v88
	v_lshlrev_b32_e32 v226, 16, v89
	v_and_b32_e32 v227, 0xffff0000, v89
	v_lshlrev_b32_e32 v228, 16, v90
	v_and_b32_e32 v229, 0xffff0000, v90
	v_lshlrev_b32_e32 v230, 16, v91
	v_and_b32_e32 v231, 0xffff0000, v91
	v_lshlrev_b32_e32 v232, 16, v92
	v_and_b32_e32 v233, 0xffff0000, v92
	v_lshlrev_b32_e32 v234, 16, v93
	v_and_b32_e32 v235, 0xffff0000, v93
	v_lshlrev_b32_e32 v236, 16, v94
	v_and_b32_e32 v237, 0xffff0000, v94
	v_lshlrev_b32_e32 v238, 16, v95
	v_and_b32_e32 v239, 0xffff0000, v95
	v_mul_f32_e32 v128, v208, v208
	v_fmac_f32_e32 v128, v209, v209
	v_mul_f32_e32 v129, v210, v210
	v_fmac_f32_e32 v129, v211, v211
	v_add_f32_e32 v128, v128, v129
	v_mul_f32_e32 v129, v212, v212
	v_fmac_f32_e32 v129, v213, v213
	v_mul_f32_e32 v132, v214, v214
	v_fmac_f32_e32 v132, v215, v215
	v_add_f32_e32 v129, v129, v132
	v_add_f32_e32 v128, v128, v129
	v_mul_f32_e32 v129, v216, v216
	v_fmac_f32_e32 v129, v217, v217
	v_mul_f32_e32 v132, v218, v218
	v_fmac_f32_e32 v132, v219, v219
	v_add_f32_e32 v129, v129, v132
	v_add_f32_e32 v128, v128, v129
	v_mul_f32_e32 v129, v220, v220
	v_fmac_f32_e32 v129, v221, v221
	v_mul_f32_e32 v132, v222, v222
	v_fmac_f32_e32 v132, v223, v223
	v_add_f32_e32 v129, v129, v132
	v_add_f32_e32 v128, v128, v129
	v_mul_f32_e32 v129, v224, v224
	v_fmac_f32_e32 v129, v225, v225
	v_mul_f32_e32 v132, v226, v226
	v_fmac_f32_e32 v132, v227, v227
	v_add_f32_e32 v129, v129, v132
	v_add_f32_e32 v128, v128, v129
	v_mul_f32_e32 v129, v228, v228
	v_fmac_f32_e32 v129, v229, v229
	v_mul_f32_e32 v132, v230, v230
	v_fmac_f32_e32 v132, v231, v231
	v_add_f32_e32 v129, v129, v132
	v_add_f32_e32 v128, v128, v129
	v_mul_f32_e32 v129, v232, v232
	v_fmac_f32_e32 v129, v233, v233
	v_mul_f32_e32 v132, v234, v234
	v_fmac_f32_e32 v132, v235, v235
	v_add_f32_e32 v129, v129, v132
	v_add_f32_e32 v128, v128, v129
	v_mul_f32_e32 v129, v236, v236
	v_fmac_f32_e32 v129, v237, v237
	v_mul_f32_e32 v132, v238, v238
	v_fmac_f32_e32 v132, v239, v239
	v_add_f32_e32 v129, v129, v132
	v_add_f32_e32 v128, v128, v129
	ds_bpermute_b32 v129, v244, v128
	s_waitcnt lgkmcnt(0)
	v_add_f32_e32 v128, v128, v129
	ds_bpermute_b32 v129, v245, v128
	s_waitcnt lgkmcnt(0)
	v_add_f32_e32 v128, v128, v129
	ds_bpermute_b32 v129, v246, v128
	s_waitcnt lgkmcnt(0)
	v_add_f32_e32 v128, v128, v129
	ds_bpermute_b32 v129, v247, v128
	s_waitcnt lgkmcnt(0)
	v_add_f32_e32 v128, v128, v129
	ds_bpermute_b32 v129, v248, v128
	s_waitcnt lgkmcnt(0)
	v_add_f32_e32 v128, v128, v129
	ds_bpermute_b32 v129, v249, v128
	s_waitcnt lgkmcnt(0)
	v_add_f32_e32 v128, v128, v129
	v_fmamk_f32 v128, v128, 0x3a000000, v255
	v_mul_f32_e32 v129, 0x4b800000, v128
	v_cmp_gt_f32_e32 vcc, s10, v128
	s_nop 1
	v_cndmask_b32_e32 v128, v128, v129, vcc
	v_rsq_f32_e32 v128, v128
	s_nop 0
	v_mul_f32_e32 v129, 0x45800000, v128
	v_cndmask_b32_e32 v130, v128, v129, vcc
	v_lshl_add_u64 v[140:141], v[250:251], 0, s[14:15]
	v_lshlrev_b32_e32 v136, 16, v64
	v_and_b32_e32 v137, 0xffff0000, v64
	v_lshlrev_b32_e32 v138, 16, v65
	v_and_b32_e32 v139, 0xffff0000, v65
	v_pk_mul_f32 v[208:209], v[130:131], v[208:209] op_sel_hi:[0,1]
	v_pk_fma_f32 v[208:209], v[0:1], v[208:209], v[136:137]
	v_pk_mul_f32 v[210:211], v[130:131], v[210:211] op_sel_hi:[0,1]
	v_pk_fma_f32 v[210:211], v[2:3], v[210:211], v[138:139]
	global_store_dwordx4 v[250:251], v[208:211], off offset:0 nt
	v_lshlrev_b32_e32 v136, 16, v66
	v_and_b32_e32 v137, 0xffff0000, v66
	v_lshlrev_b32_e32 v138, 16, v67
	v_and_b32_e32 v139, 0xffff0000, v67
	v_pk_mul_f32 v[212:213], v[130:131], v[212:213] op_sel_hi:[0,1]
	v_pk_fma_f32 v[212:213], v[4:5], v[212:213], v[136:137]
	v_pk_mul_f32 v[214:215], v[130:131], v[214:215] op_sel_hi:[0,1]
	v_pk_fma_f32 v[214:215], v[6:7], v[214:215], v[138:139]
	global_store_dwordx4 v[250:251], v[212:215], off offset:1024 nt
	v_lshlrev_b32_e32 v136, 16, v68
	v_and_b32_e32 v137, 0xffff0000, v68
	v_lshlrev_b32_e32 v138, 16, v69
	v_and_b32_e32 v139, 0xffff0000, v69
	v_pk_mul_f32 v[216:217], v[130:131], v[216:217] op_sel_hi:[0,1]
	v_pk_fma_f32 v[216:217], v[8:9], v[216:217], v[136:137]
	v_pk_mul_f32 v[218:219], v[130:131], v[218:219] op_sel_hi:[0,1]
	v_pk_fma_f32 v[218:219], v[10:11], v[218:219], v[138:139]
	global_store_dwordx4 v[250:251], v[216:219], off offset:2048 nt
	v_lshlrev_b32_e32 v136, 16, v70
	v_and_b32_e32 v137, 0xffff0000, v70
	v_lshlrev_b32_e32 v138, 16, v71
	v_and_b32_e32 v139, 0xffff0000, v71
	v_pk_mul_f32 v[220:221], v[130:131], v[220:221] op_sel_hi:[0,1]
	v_pk_fma_f32 v[220:221], v[12:13], v[220:221], v[136:137]
	v_pk_mul_f32 v[222:223], v[130:131], v[222:223] op_sel_hi:[0,1]
	v_pk_fma_f32 v[222:223], v[14:15], v[222:223], v[138:139]
	global_store_dwordx4 v[250:251], v[220:223], off offset:3072 nt
	v_lshlrev_b32_e32 v136, 16, v72
	v_and_b32_e32 v137, 0xffff0000, v72
	v_lshlrev_b32_e32 v138, 16, v73
	v_and_b32_e32 v139, 0xffff0000, v73
	v_pk_mul_f32 v[224:225], v[130:131], v[224:225] op_sel_hi:[0,1]
	v_pk_fma_f32 v[224:225], v[16:17], v[224:225], v[136:137]
	v_pk_mul_f32 v[226:227], v[130:131], v[226:227] op_sel_hi:[0,1]
	v_pk_fma_f32 v[226:227], v[18:19], v[226:227], v[138:139]
	global_store_dwordx4 v[140:141], v[224:227], off offset:0 nt
	v_lshlrev_b32_e32 v136, 16, v74
	v_and_b32_e32 v137, 0xffff0000, v74
	v_lshlrev_b32_e32 v138, 16, v75
	v_and_b32_e32 v139, 0xffff0000, v75
	v_pk_mul_f32 v[228:229], v[130:131], v[228:229] op_sel_hi:[0,1]
	v_pk_fma_f32 v[228:229], v[20:21], v[228:229], v[136:137]
	v_pk_mul_f32 v[230:231], v[130:131], v[230:231] op_sel_hi:[0,1]
	v_pk_fma_f32 v[230:231], v[22:23], v[230:231], v[138:139]
	global_store_dwordx4 v[140:141], v[228:231], off offset:1024 nt
	v_lshlrev_b32_e32 v136, 16, v76
	v_and_b32_e32 v137, 0xffff0000, v76
	v_lshlrev_b32_e32 v138, 16, v77
	v_and_b32_e32 v139, 0xffff0000, v77
	v_pk_mul_f32 v[232:233], v[130:131], v[232:233] op_sel_hi:[0,1]
	v_pk_fma_f32 v[232:233], v[24:25], v[232:233], v[136:137]
	v_pk_mul_f32 v[234:235], v[130:131], v[234:235] op_sel_hi:[0,1]
	v_pk_fma_f32 v[234:235], v[26:27], v[234:235], v[138:139]
	global_store_dwordx4 v[140:141], v[232:235], off offset:2048 nt
	v_lshlrev_b32_e32 v136, 16, v78
	v_and_b32_e32 v137, 0xffff0000, v78
	v_lshlrev_b32_e32 v138, 16, v79
	v_and_b32_e32 v139, 0xffff0000, v79
	v_pk_mul_f32 v[236:237], v[130:131], v[236:237] op_sel_hi:[0,1]
	v_pk_fma_f32 v[236:237], v[28:29], v[236:237], v[136:137]
	v_pk_mul_f32 v[238:239], v[130:131], v[238:239] op_sel_hi:[0,1]
	v_pk_fma_f32 v[238:239], v[30:31], v[238:239], v[138:139]
	global_store_dwordx4 v[140:141], v[236:239], off offset:3072 nt
	v_lshl_add_u64 v[250:251], v[250:251], 0, s[12:13]
	s_waitcnt vmcnt(32)
	s_cmpk_gt_i32 s11, 1
	s_cbranch_scc1 .Lp15_no5a
	global_load_dwordx2 v[176:177], v252, s[0:1] offset:0 nt
	global_load_dwordx2 v[178:179], v252, s[0:1] offset:512 nt
	global_load_dwordx2 v[180:181], v252, s[0:1] offset:1024 nt
	global_load_dwordx2 v[182:183], v252, s[0:1] offset:1536 nt
	global_load_dwordx2 v[184:185], v252, s[0:1] offset:2048 nt
	global_load_dwordx2 v[186:187], v252, s[0:1] offset:2560 nt
	global_load_dwordx2 v[188:189], v252, s[0:1] offset:3072 nt
	global_load_dwordx2 v[190:191], v252, s[0:1] offset:3584 nt
	global_load_dwordx2 v[192:193], v252, s[2:3] offset:0 nt
	global_load_dwordx2 v[194:195], v252, s[2:3] offset:512 nt
	global_load_dwordx2 v[196:197], v252, s[2:3] offset:1024 nt
	global_load_dwordx2 v[198:199], v252, s[2:3] offset:1536 nt
	global_load_dwordx2 v[200:201], v252, s[2:3] offset:2048 nt
	global_load_dwordx2 v[202:203], v252, s[2:3] offset:2560 nt
	global_load_dwordx2 v[204:205], v252, s[2:3] offset:3072 nt
	global_load_dwordx2 v[206:207], v252, s[2:3] offset:3584 nt
	s_add_u32 s0, s0, 0x8000
	s_addc_u32 s1, s1, 0
	s_add_u32 s2, s2, 0x8000
	s_addc_u32 s3, s3, 0
.Lp15_no5a:
	v_lshlrev_b32_e32 v208, 16, v112
	v_and_b32_e32 v209, 0xffff0000, v112
	v_lshlrev_b32_e32 v210, 16, v113
	v_and_b32_e32 v211, 0xffff0000, v113
	v_lshlrev_b32_e32 v212, 16, v114
	v_and_b32_e32 v213, 0xffff0000, v114
	v_lshlrev_b32_e32 v214, 16, v115
	v_and_b32_e32 v215, 0xffff0000, v115
	v_lshlrev_b32_e32 v216, 16, v116
	v_and_b32_e32 v217, 0xffff0000, v116
	v_lshlrev_b32_e32 v218, 16, v117
	v_and_b32_e32 v219, 0xffff0000, v117
	v_lshlrev_b32_e32 v220, 16, v118
	v_and_b32_e32 v221, 0xffff0000, v118
	v_lshlrev_b32_e32 v222, 16, v119
	v_and_b32_e32 v223, 0xffff0000, v119
	v_lshlrev_b32_e32 v224, 16, v120
	v_and_b32_e32 v225, 0xffff0000, v120
	v_lshlrev_b32_e32 v226, 16, v121
	v_and_b32_e32 v227, 0xffff0000, v121
	v_lshlrev_b32_e32 v228, 16, v122
	v_and_b32_e32 v229, 0xffff0000, v122
	v_lshlrev_b32_e32 v230, 16, v123
	v_and_b32_e32 v231, 0xffff0000, v123
	v_lshlrev_b32_e32 v232, 16, v124
	v_and_b32_e32 v233, 0xffff0000, v124
	v_lshlrev_b32_e32 v234, 16, v125
	v_and_b32_e32 v235, 0xffff0000, v125
	v_lshlrev_b32_e32 v236, 16, v126
	v_and_b32_e32 v237, 0xffff0000, v126
	v_lshlrev_b32_e32 v238, 16, v127
	v_and_b32_e32 v239, 0xffff0000, v127
	v_mul_f32_e32 v128, v208, v208
	v_fmac_f32_e32 v128, v209, v209
	v_mul_f32_e32 v129, v210, v210
	v_fmac_f32_e32 v129, v211, v211
	v_add_f32_e32 v128, v128, v129
	v_mul_f32_e32 v129, v212, v212
	v_fmac_f32_e32 v129, v213, v213
	v_mul_f32_e32 v132, v214, v214
	v_fmac_f32_e32 v132, v215, v215
	v_add_f32_e32 v129, v129, v132
	v_add_f32_e32 v128, v128, v129
	v_mul_f32_e32 v129, v216, v216
	v_fmac_f32_e32 v129, v217, v217
	v_mul_f32_e32 v132, v218, v218
	v_fmac_f32_e32 v132, v219, v219
	v_add_f32_e32 v129, v129, v132
	v_add_f32_e32 v128, v128, v129
	v_mul_f32_e32 v129, v220, v220
	v_fmac_f32_e32 v129, v221, v221
	v_mul_f32_e32 v132, v222, v222
	v_fmac_f32_e32 v132, v223, v223
	v_add_f32_e32 v129, v129, v132
	v_add_f32_e32 v128, v128, v129
	v_mul_f32_e32 v129, v224, v224
	v_fmac_f32_e32 v129, v225, v225
	v_mul_f32_e32 v132, v226, v226
	v_fmac_f32_e32 v132, v227, v227
	v_add_f32_e32 v129, v129, v132
	v_add_f32_e32 v128, v128, v129
	v_mul_f32_e32 v129, v228, v228
	v_fmac_f32_e32 v129, v229, v229
	v_mul_f32_e32 v132, v230, v230
	v_fmac_f32_e32 v132, v231, v231
	v_add_f32_e32 v129, v129, v132
	v_add_f32_e32 v128, v128, v129
	v_mul_f32_e32 v129, v232, v232
	v_fmac_f32_e32 v129, v233, v233
	v_mul_f32_e32 v132, v234, v234
	v_fmac_f32_e32 v132, v235, v235
	v_add_f32_e32 v129, v129, v132
	v_add_f32_e32 v128, v128, v129
	v_mul_f32_e32 v129, v236, v236
	v_fmac_f32_e32 v129, v237, v237
	v_mul_f32_e32 v132, v238, v238
	v_fmac_f32_e32 v132, v239, v239
	v_add_f32_e32 v129, v129, v132
	v_add_f32_e32 v128, v128, v129
	ds_bpermute_b32 v129, v244, v128
	s_waitcnt lgkmcnt(0)
	v_add_f32_e32 v128, v128, v129
	ds_bpermute_b32 v129, v245, v128
	s_waitcnt lgkmcnt(0)
	v_add_f32_e32 v128, v128, v129
	ds_bpermute_b32 v129, v246, v128
	s_waitcnt lgkmcnt(0)
	v_add_f32_e32 v128, v128, v129
	ds_bpermute_b32 v129, v247, v128
	s_waitcnt lgkmcnt(0)
	v_add_f32_e32 v128, v128, v129
	ds_bpermute_b32 v129, v248, v128
	s_waitcnt lgkmcnt(0)
	v_add_f32_e32 v128, v128, v129
	ds_bpermute_b32 v129, v249, v128
	s_waitcnt lgkmcnt(0)
	v_add_f32_e32 v128, v128, v129
	v_fmamk_f32 v128, v128, 0x3a000000, v255
	v_mul_f32_e32 v129, 0x4b800000, v128
	v_cmp_gt_f32_e32 vcc, s10, v128
	s_nop 1
	v_cndmask_b32_e32 v128, v128, v129, vcc
	v_rsq_f32_e32 v128, v128
	s_nop 0
	v_mul_f32_e32 v129, 0x45800000, v128
	v_cndmask_b32_e32 v130, v128, v129, vcc
	v_lshl_add_u64 v[140:141], v[250:251], 0, s[14:15]
	v_lshlrev_b32_e32 v136, 16, v96
	v_and_b32_e32 v137, 0xffff0000, v96
	v_lshlrev_b32_e32 v138, 16, v97
	v_and_b32_e32 v139, 0xffff0000, v97
	v_pk_mul_f32 v[208:209], v[130:131], v[208:209] op_sel_hi:[0,1]
	v_pk_fma_f32 v[208:209], v[0:1], v[208:209], v[136:137]
	v_pk_mul_f32 v[210:211], v[130:131], v[210:211] op_sel_hi:[0,1]
	v_pk_fma_f32 v[210:211], v[2:3], v[210:211], v[138:139]
	global_store_dwordx4 v[250:251], v[208:211], off offset:0 nt
	v_lshlrev_b32_e32 v136, 16, v98
	v_and_b32_e32 v137, 0xffff0000, v98
	v_lshlrev_b32_e32 v138, 16, v99
	v_and_b32_e32 v139, 0xffff0000, v99
	v_pk_mul_f32 v[212:213], v[130:131], v[212:213] op_sel_hi:[0,1]
	v_pk_fma_f32 v[212:213], v[4:5], v[212:213], v[136:137]
	v_pk_mul_f32 v[214:215], v[130:131], v[214:215] op_sel_hi:[0,1]
	v_pk_fma_f32 v[214:215], v[6:7], v[214:215], v[138:139]
	global_store_dwordx4 v[250:251], v[212:215], off offset:1024 nt
	v_lshlrev_b32_e32 v136, 16, v100
	v_and_b32_e32 v137, 0xffff0000, v100
	v_lshlrev_b32_e32 v138, 16, v101
	v_and_b32_e32 v139, 0xffff0000, v101
	v_pk_mul_f32 v[216:217], v[130:131], v[216:217] op_sel_hi:[0,1]
	v_pk_fma_f32 v[216:217], v[8:9], v[216:217], v[136:137]
	v_pk_mul_f32 v[218:219], v[130:131], v[218:219] op_sel_hi:[0,1]
	v_pk_fma_f32 v[218:219], v[10:11], v[218:219], v[138:139]
	global_store_dwordx4 v[250:251], v[216:219], off offset:2048 nt
	v_lshlrev_b32_e32 v136, 16, v102
	v_and_b32_e32 v137, 0xffff0000, v102
	v_lshlrev_b32_e32 v138, 16, v103
	v_and_b32_e32 v139, 0xffff0000, v103
	v_pk_mul_f32 v[220:221], v[130:131], v[220:221] op_sel_hi:[0,1]
	v_pk_fma_f32 v[220:221], v[12:13], v[220:221], v[136:137]
	v_pk_mul_f32 v[222:223], v[130:131], v[222:223] op_sel_hi:[0,1]
	v_pk_fma_f32 v[222:223], v[14:15], v[222:223], v[138:139]
	global_store_dwordx4 v[250:251], v[220:223], off offset:3072 nt
	v_lshlrev_b32_e32 v136, 16, v104
	v_and_b32_e32 v137, 0xffff0000, v104
	v_lshlrev_b32_e32 v138, 16, v105
	v_and_b32_e32 v139, 0xffff0000, v105
	v_pk_mul_f32 v[224:225], v[130:131], v[224:225] op_sel_hi:[0,1]
	v_pk_fma_f32 v[224:225], v[16:17], v[224:225], v[136:137]
	v_pk_mul_f32 v[226:227], v[130:131], v[226:227] op_sel_hi:[0,1]
	v_pk_fma_f32 v[226:227], v[18:19], v[226:227], v[138:139]
	global_store_dwordx4 v[140:141], v[224:227], off offset:0 nt
	v_lshlrev_b32_e32 v136, 16, v106
	v_and_b32_e32 v137, 0xffff0000, v106
	v_lshlrev_b32_e32 v138, 16, v107
	v_and_b32_e32 v139, 0xffff0000, v107
	v_pk_mul_f32 v[228:229], v[130:131], v[228:229] op_sel_hi:[0,1]
	v_pk_fma_f32 v[228:229], v[20:21], v[228:229], v[136:137]
	v_pk_mul_f32 v[230:231], v[130:131], v[230:231] op_sel_hi:[0,1]
	v_pk_fma_f32 v[230:231], v[22:23], v[230:231], v[138:139]
	global_store_dwordx4 v[140:141], v[228:231], off offset:1024 nt
	v_lshlrev_b32_e32 v136, 16, v108
	v_and_b32_e32 v137, 0xffff0000, v108
	v_lshlrev_b32_e32 v138, 16, v109
	v_and_b32_e32 v139, 0xffff0000, v109
	v_pk_mul_f32 v[232:233], v[130:131], v[232:233] op_sel_hi:[0,1]
	v_pk_fma_f32 v[232:233], v[24:25], v[232:233], v[136:137]
	v_pk_mul_f32 v[234:235], v[130:131], v[234:235] op_sel_hi:[0,1]
	v_pk_fma_f32 v[234:235], v[26:27], v[234:235], v[138:139]
	global_store_dwordx4 v[140:141], v[232:235], off offset:2048 nt
	v_lshlrev_b32_e32 v136, 16, v110
	v_and_b32_e32 v137, 0xffff0000, v110
	v_lshlrev_b32_e32 v138, 16, v111
	v_and_b32_e32 v139, 0xffff0000, v111
	v_pk_mul_f32 v[236:237], v[130:131], v[236:237] op_sel_hi:[0,1]
	v_pk_fma_f32 v[236:237], v[28:29], v[236:237], v[136:137]
	v_pk_mul_f32 v[238:239], v[130:131], v[238:239] op_sel_hi:[0,1]
	v_pk_fma_f32 v[238:239], v[30:31], v[238:239], v[138:139]
	global_store_dwordx4 v[140:141], v[236:239], off offset:3072 nt
	v_lshl_add_u64 v[250:251], v[250:251], 0, s[12:13]
	s_waitcnt vmcnt(16)
	v_lshlrev_b32_e32 v208, 16, v160
	v_and_b32_e32 v209, 0xffff0000, v160
	v_lshlrev_b32_e32 v210, 16, v161
	v_and_b32_e32 v211, 0xffff0000, v161
	v_lshlrev_b32_e32 v212, 16, v162
	v_and_b32_e32 v213, 0xffff0000, v162
	v_lshlrev_b32_e32 v214, 16, v163
	v_and_b32_e32 v215, 0xffff0000, v163
	v_lshlrev_b32_e32 v216, 16, v164
	v_and_b32_e32 v217, 0xffff0000, v164
	v_lshlrev_b32_e32 v218, 16, v165
	v_and_b32_e32 v219, 0xffff0000, v165
	v_lshlrev_b32_e32 v220, 16, v166
	v_and_b32_e32 v221, 0xffff0000, v166
	v_lshlrev_b32_e32 v222, 16, v167
	v_and_b32_e32 v223, 0xffff0000, v167
	v_lshlrev_b32_e32 v224, 16, v168
	v_and_b32_e32 v225, 0xffff0000, v168
	v_lshlrev_b32_e32 v226, 16, v169
	v_and_b32_e32 v227, 0xffff0000, v169
	v_lshlrev_b32_e32 v228, 16, v170
	v_and_b32_e32 v229, 0xffff0000, v170
	v_lshlrev_b32_e32 v230, 16, v171
	v_and_b32_e32 v231, 0xffff0000, v171
	v_lshlrev_b32_e32 v232, 16, v172
	v_and_b32_e32 v233, 0xffff0000, v172
	v_lshlrev_b32_e32 v234, 16, v173
	v_and_b32_e32 v235, 0xffff0000, v173
	v_lshlrev_b32_e32 v236, 16, v174
	v_and_b32_e32 v237, 0xffff0000, v174
	v_lshlrev_b32_e32 v238, 16, v175
	v_and_b32_e32 v239, 0xffff0000, v175
	v_mul_f32_e32 v128, v208, v208
	v_fmac_f32_e32 v128, v209, v209
	v_mul_f32_e32 v129, v210, v210
	v_fmac_f32_e32 v129, v211, v211
	v_add_f32_e32 v128, v128, v129
	v_mul_f32_e32 v129, v212, v212
	v_fmac_f32_e32 v129, v213, v213
	v_mul_f32_e32 v132, v214, v214
	v_fmac_f32_e32 v132, v215, v215
	v_add_f32_e32 v129, v129, v132
	v_add_f32_e32 v128, v128, v129
	v_mul_f32_e32 v129, v216, v216
	v_fmac_f32_e32 v129, v217, v217
	v_mul_f32_e32 v132, v218, v218
	v_fmac_f32_e32 v132, v219, v219
	v_add_f32_e32 v129, v129, v132
	v_add_f32_e32 v128, v128, v129
	v_mul_f32_e32 v129, v220, v220
	v_fmac_f32_e32 v129, v221, v221
	v_mul_f32_e32 v132, v222, v222
	v_fmac_f32_e32 v132, v223, v223
	v_add_f32_e32 v129, v129, v132
	v_add_f32_e32 v128, v128, v129
	v_mul_f32_e32 v129, v224, v224
	v_fmac_f32_e32 v129, v225, v225
	v_mul_f32_e32 v132, v226, v226
	v_fmac_f32_e32 v132, v227, v227
	v_add_f32_e32 v129, v129, v132
	v_add_f32_e32 v128, v128, v129
	v_mul_f32_e32 v129, v228, v228
	v_fmac_f32_e32 v129, v229, v229
	v_mul_f32_e32 v132, v230, v230
	v_fmac_f32_e32 v132, v231, v231
	v_add_f32_e32 v129, v129, v132
	v_add_f32_e32 v128, v128, v129
	v_mul_f32_e32 v129, v232, v232
	v_fmac_f32_e32 v129, v233, v233
	v_mul_f32_e32 v132, v234, v234
	v_fmac_f32_e32 v132, v235, v235
	v_add_f32_e32 v129, v129, v132
	v_add_f32_e32 v128, v128, v129
	v_mul_f32_e32 v129, v236, v236
	v_fmac_f32_e32 v129, v237, v237
	v_mul_f32_e32 v132, v238, v238
	v_fmac_f32_e32 v132, v239, v239
	v_add_f32_e32 v129, v129, v132
	v_add_f32_e32 v128, v128, v129
	ds_bpermute_b32 v129, v244, v128
	s_waitcnt lgkmcnt(0)
	v_add_f32_e32 v128, v128, v129
	ds_bpermute_b32 v129, v245, v128
	s_waitcnt lgkmcnt(0)
	v_add_f32_e32 v128, v128, v129
	ds_bpermute_b32 v129, v246, v128
	s_waitcnt lgkmcnt(0)
	v_add_f32_e32 v128, v128, v129
	ds_bpermute_b32 v129, v247, v128
	s_waitcnt lgkmcnt(0)
	v_add_f32_e32 v128, v128, v129
	ds_bpermute_b32 v129, v248, v128
	s_waitcnt lgkmcnt(0)
	v_add_f32_e32 v128, v128, v129
	ds_bpermute_b32 v129, v249, v128
	s_waitcnt lgkmcnt(0)
	v_add_f32_e32 v128, v128, v129
	v_fmamk_f32 v128, v128, 0x3a000000, v255
	v_mul_f32_e32 v129, 0x4b800000, v128
	v_cmp_gt_f32_e32 vcc, s10, v128
	s_nop 1
	v_cndmask_b32_e32 v128, v128, v129, vcc
	v_rsq_f32_e32 v128, v128
	s_nop 0
	v_mul_f32_e32 v129, 0x45800000, v128
	v_cndmask_b32_e32 v130, v128, v129, vcc
	v_lshl_add_u64 v[140:141], v[250:251], 0, s[14:15]
	v_lshlrev_b32_e32 v136, 16, v144
	v_and_b32_e32 v137, 0xffff0000, v144
	v_lshlrev_b32_e32 v138, 16, v145
	v_and_b32_e32 v139, 0xffff0000, v145
	v_pk_mul_f32 v[208:209], v[130:131], v[208:209] op_sel_hi:[0,1]
	v_pk_fma_f32 v[208:209], v[0:1], v[208:209], v[136:137]
	v_pk_mul_f32 v[210:211], v[130:131], v[210:211] op_sel_hi:[0,1]
	v_pk_fma_f32 v[210:211], v[2:3], v[210:211], v[138:139]
	global_store_dwordx4 v[250:251], v[208:211], off offset:0 nt
	v_lshlrev_b32_e32 v136, 16, v146
	v_and_b32_e32 v137, 0xffff0000, v146
	v_lshlrev_b32_e32 v138, 16, v147
	v_and_b32_e32 v139, 0xffff0000, v147
	v_pk_mul_f32 v[212:213], v[130:131], v[212:213] op_sel_hi:[0,1]
	v_pk_fma_f32 v[212:213], v[4:5], v[212:213], v[136:137]
	v_pk_mul_f32 v[214:215], v[130:131], v[214:215] op_sel_hi:[0,1]
	v_pk_fma_f32 v[214:215], v[6:7], v[214:215], v[138:139]
	global_store_dwordx4 v[250:251], v[212:215], off offset:1024 nt
	v_lshlrev_b32_e32 v136, 16, v148
	v_and_b32_e32 v137, 0xffff0000, v148
	v_lshlrev_b32_e32 v138, 16, v149
	v_and_b32_e32 v139, 0xffff0000, v149
	v_pk_mul_f32 v[216:217], v[130:131], v[216:217] op_sel_hi:[0,1]
	v_pk_fma_f32 v[216:217], v[8:9], v[216:217], v[136:137]
	v_pk_mul_f32 v[218:219], v[130:131], v[218:219] op_sel_hi:[0,1]
	v_pk_fma_f32 v[218:219], v[10:11], v[218:219], v[138:139]
	global_store_dwordx4 v[250:251], v[216:219], off offset:2048 nt
	v_lshlrev_b32_e32 v136, 16, v150
	v_and_b32_e32 v137, 0xffff0000, v150
	v_lshlrev_b32_e32 v138, 16, v151
	v_and_b32_e32 v139, 0xffff0000, v151
	v_pk_mul_f32 v[220:221], v[130:131], v[220:221] op_sel_hi:[0,1]
	v_pk_fma_f32 v[220:221], v[12:13], v[220:221], v[136:137]
	v_pk_mul_f32 v[222:223], v[130:131], v[222:223] op_sel_hi:[0,1]
	v_pk_fma_f32 v[222:223], v[14:15], v[222:223], v[138:139]
	global_store_dwordx4 v[250:251], v[220:223], off offset:3072 nt
	v_lshlrev_b32_e32 v136, 16, v152
	v_and_b32_e32 v137, 0xffff0000, v152
	v_lshlrev_b32_e32 v138, 16, v153
	v_and_b32_e32 v139, 0xffff0000, v153
	v_pk_mul_f32 v[224:225], v[130:131], v[224:225] op_sel_hi:[0,1]
	v_pk_fma_f32 v[224:225], v[16:17], v[224:225], v[136:137]
	v_pk_mul_f32 v[226:227], v[130:131], v[226:227] op_sel_hi:[0,1]
	v_pk_fma_f32 v[226:227], v[18:19], v[226:227], v[138:139]
	global_store_dwordx4 v[140:141], v[224:227], off offset:0 nt
	v_lshlrev_b32_e32 v136, 16, v154
	v_and_b32_e32 v137, 0xffff0000, v154
	v_lshlrev_b32_e32 v138, 16, v155
	v_and_b32_e32 v139, 0xffff0000, v155
	v_pk_mul_f32 v[228:229], v[130:131], v[228:229] op_sel_hi:[0,1]
	v_pk_fma_f32 v[228:229], v[20:21], v[228:229], v[136:137]
	v_pk_mul_f32 v[230:231], v[130:131], v[230:231] op_sel_hi:[0,1]
	v_pk_fma_f32 v[230:231], v[22:23], v[230:231], v[138:139]
	global_store_dwordx4 v[140:141], v[228:231], off offset:1024 nt
	v_lshlrev_b32_e32 v136, 16, v156
	v_and_b32_e32 v137, 0xffff0000, v156
	v_lshlrev_b32_e32 v138, 16, v157
	v_and_b32_e32 v139, 0xffff0000, v157
	v_pk_mul_f32 v[232:233], v[130:131], v[232:233] op_sel_hi:[0,1]
	v_pk_fma_f32 v[232:233], v[24:25], v[232:233], v[136:137]
	v_pk_mul_f32 v[234:235], v[130:131], v[234:235] op_sel_hi:[0,1]
	v_pk_fma_f32 v[234:235], v[26:27], v[234:235], v[138:139]
	global_store_dwordx4 v[140:141], v[232:235], off offset:2048 nt
	v_lshlrev_b32_e32 v136, 16, v158
	v_and_b32_e32 v137, 0xffff0000, v158
	v_lshlrev_b32_e32 v138, 16, v159
	v_and_b32_e32 v139, 0xffff0000, v159
	v_pk_mul_f32 v[236:237], v[130:131], v[236:237] op_sel_hi:[0,1]
	v_pk_fma_f32 v[236:237], v[28:29], v[236:237], v[136:137]
	v_pk_mul_f32 v[238:239], v[130:131], v[238:239] op_sel_hi:[0,1]
	v_pk_fma_f32 v[238:239], v[30:31], v[238:239], v[138:139]
	global_store_dwordx4 v[140:141], v[236:239], off offset:3072 nt
	v_lshl_add_u64 v[250:251], v[250:251], 0, s[12:13]
	s_cmpk_gt_i32 s11, 1
	s_cbranch_scc1 .LBB0_1608
	s_waitcnt vmcnt(16)
	v_lshlrev_b32_e32 v208, 16, v192
	v_and_b32_e32 v209, 0xffff0000, v192
	v_lshlrev_b32_e32 v210, 16, v193
	v_and_b32_e32 v211, 0xffff0000, v193
	v_lshlrev_b32_e32 v212, 16, v194
	v_and_b32_e32 v213, 0xffff0000, v194
	v_lshlrev_b32_e32 v214, 16, v195
	v_and_b32_e32 v215, 0xffff0000, v195
	v_lshlrev_b32_e32 v216, 16, v196
	v_and_b32_e32 v217, 0xffff0000, v196
	v_lshlrev_b32_e32 v218, 16, v197
	v_and_b32_e32 v219, 0xffff0000, v197
	v_lshlrev_b32_e32 v220, 16, v198
	v_and_b32_e32 v221, 0xffff0000, v198
	v_lshlrev_b32_e32 v222, 16, v199
	v_and_b32_e32 v223, 0xffff0000, v199
	v_lshlrev_b32_e32 v224, 16, v200
	v_and_b32_e32 v225, 0xffff0000, v200
	v_lshlrev_b32_e32 v226, 16, v201
	v_and_b32_e32 v227, 0xffff0000, v201
	v_lshlrev_b32_e32 v228, 16, v202
	v_and_b32_e32 v229, 0xffff0000, v202
	v_lshlrev_b32_e32 v230, 16, v203
	v_and_b32_e32 v231, 0xffff0000, v203
	v_lshlrev_b32_e32 v232, 16, v204
	v_and_b32_e32 v233, 0xffff0000, v204
	v_lshlrev_b32_e32 v234, 16, v205
	v_and_b32_e32 v235, 0xffff0000, v205
	v_lshlrev_b32_e32 v236, 16, v206
	v_and_b32_e32 v237, 0xffff0000, v206
	v_lshlrev_b32_e32 v238, 16, v207
	v_and_b32_e32 v239, 0xffff0000, v207
	v_mul_f32_e32 v128, v208, v208
	v_fmac_f32_e32 v128, v209, v209
	v_mul_f32_e32 v129, v210, v210
	v_fmac_f32_e32 v129, v211, v211
	v_add_f32_e32 v128, v128, v129
	v_mul_f32_e32 v129, v212, v212
	v_fmac_f32_e32 v129, v213, v213
	v_mul_f32_e32 v132, v214, v214
	v_fmac_f32_e32 v132, v215, v215
	v_add_f32_e32 v129, v129, v132
	v_add_f32_e32 v128, v128, v129
	v_mul_f32_e32 v129, v216, v216
	v_fmac_f32_e32 v129, v217, v217
	v_mul_f32_e32 v132, v218, v218
	v_fmac_f32_e32 v132, v219, v219
	v_add_f32_e32 v129, v129, v132
	v_add_f32_e32 v128, v128, v129
	v_mul_f32_e32 v129, v220, v220
	v_fmac_f32_e32 v129, v221, v221
	v_mul_f32_e32 v132, v222, v222
	v_fmac_f32_e32 v132, v223, v223
	v_add_f32_e32 v129, v129, v132
	v_add_f32_e32 v128, v128, v129
	v_mul_f32_e32 v129, v224, v224
	v_fmac_f32_e32 v129, v225, v225
	v_mul_f32_e32 v132, v226, v226
	v_fmac_f32_e32 v132, v227, v227
	v_add_f32_e32 v129, v129, v132
	v_add_f32_e32 v128, v128, v129
	v_mul_f32_e32 v129, v228, v228
	v_fmac_f32_e32 v129, v229, v229
	v_mul_f32_e32 v132, v230, v230
	v_fmac_f32_e32 v132, v231, v231
	v_add_f32_e32 v129, v129, v132
	v_add_f32_e32 v128, v128, v129
	v_mul_f32_e32 v129, v232, v232
	v_fmac_f32_e32 v129, v233, v233
	v_mul_f32_e32 v132, v234, v234
	v_fmac_f32_e32 v132, v235, v235
	v_add_f32_e32 v129, v129, v132
	v_add_f32_e32 v128, v128, v129
	v_mul_f32_e32 v129, v236, v236
	v_fmac_f32_e32 v129, v237, v237
	v_mul_f32_e32 v132, v238, v238
	v_fmac_f32_e32 v132, v239, v239
	v_add_f32_e32 v129, v129, v132
	v_add_f32_e32 v128, v128, v129
	ds_bpermute_b32 v129, v244, v128
	s_waitcnt lgkmcnt(0)
	v_add_f32_e32 v128, v128, v129
	ds_bpermute_b32 v129, v245, v128
	s_waitcnt lgkmcnt(0)
	v_add_f32_e32 v128, v128, v129
	ds_bpermute_b32 v129, v246, v128
	s_waitcnt lgkmcnt(0)
	v_add_f32_e32 v128, v128, v129
	ds_bpermute_b32 v129, v247, v128
	s_waitcnt lgkmcnt(0)
	v_add_f32_e32 v128, v128, v129
	ds_bpermute_b32 v129, v248, v128
	s_waitcnt lgkmcnt(0)
	v_add_f32_e32 v128, v128, v129
	ds_bpermute_b32 v129, v249, v128
	s_waitcnt lgkmcnt(0)
	v_add_f32_e32 v128, v128, v129
	v_fmamk_f32 v128, v128, 0x3a000000, v255
	v_mul_f32_e32 v129, 0x4b800000, v128
	v_cmp_gt_f32_e32 vcc, s10, v128
	s_nop 1
	v_cndmask_b32_e32 v128, v128, v129, vcc
	v_rsq_f32_e32 v128, v128
	s_nop 0
	v_mul_f32_e32 v129, 0x45800000, v128
	v_cndmask_b32_e32 v130, v128, v129, vcc
	v_lshl_add_u64 v[140:141], v[250:251], 0, s[14:15]
	v_lshlrev_b32_e32 v136, 16, v176
	v_and_b32_e32 v137, 0xffff0000, v176
	v_lshlrev_b32_e32 v138, 16, v177
	v_and_b32_e32 v139, 0xffff0000, v177
	v_pk_mul_f32 v[208:209], v[130:131], v[208:209] op_sel_hi:[0,1]
	v_pk_fma_f32 v[208:209], v[0:1], v[208:209], v[136:137]
	v_pk_mul_f32 v[210:211], v[130:131], v[210:211] op_sel_hi:[0,1]
	v_pk_fma_f32 v[210:211], v[2:3], v[210:211], v[138:139]
	global_store_dwordx4 v[250:251], v[208:211], off offset:0 nt
	v_lshlrev_b32_e32 v136, 16, v178
	v_and_b32_e32 v137, 0xffff0000, v178
	v_lshlrev_b32_e32 v138, 16, v179
	v_and_b32_e32 v139, 0xffff0000, v179
	v_pk_mul_f32 v[212:213], v[130:131], v[212:213] op_sel_hi:[0,1]
	v_pk_fma_f32 v[212:213], v[4:5], v[212:213], v[136:137]
	v_pk_mul_f32 v[214:215], v[130:131], v[214:215] op_sel_hi:[0,1]
	v_pk_fma_f32 v[214:215], v[6:7], v[214:215], v[138:139]
	global_store_dwordx4 v[250:251], v[212:215], off offset:1024 nt
	v_lshlrev_b32_e32 v136, 16, v180
	v_and_b32_e32 v137, 0xffff0000, v180
	v_lshlrev_b32_e32 v138, 16, v181
	v_and_b32_e32 v139, 0xffff0000, v181
	v_pk_mul_f32 v[216:217], v[130:131], v[216:217] op_sel_hi:[0,1]
	v_pk_fma_f32 v[216:217], v[8:9], v[216:217], v[136:137]
	v_pk_mul_f32 v[218:219], v[130:131], v[218:219] op_sel_hi:[0,1]
	v_pk_fma_f32 v[218:219], v[10:11], v[218:219], v[138:139]
	global_store_dwordx4 v[250:251], v[216:219], off offset:2048 nt
	v_lshlrev_b32_e32 v136, 16, v182
	v_and_b32_e32 v137, 0xffff0000, v182
	v_lshlrev_b32_e32 v138, 16, v183
	v_and_b32_e32 v139, 0xffff0000, v183
	v_pk_mul_f32 v[220:221], v[130:131], v[220:221] op_sel_hi:[0,1]
	v_pk_fma_f32 v[220:221], v[12:13], v[220:221], v[136:137]
	v_pk_mul_f32 v[222:223], v[130:131], v[222:223] op_sel_hi:[0,1]
	v_pk_fma_f32 v[222:223], v[14:15], v[222:223], v[138:139]
	global_store_dwordx4 v[250:251], v[220:223], off offset:3072 nt
	v_lshlrev_b32_e32 v136, 16, v184
	v_and_b32_e32 v137, 0xffff0000, v184
	v_lshlrev_b32_e32 v138, 16, v185
	v_and_b32_e32 v139, 0xffff0000, v185
	v_pk_mul_f32 v[224:225], v[130:131], v[224:225] op_sel_hi:[0,1]
	v_pk_fma_f32 v[224:225], v[16:17], v[224:225], v[136:137]
	v_pk_mul_f32 v[226:227], v[130:131], v[226:227] op_sel_hi:[0,1]
	v_pk_fma_f32 v[226:227], v[18:19], v[226:227], v[138:139]
	global_store_dwordx4 v[140:141], v[224:227], off offset:0 nt
	v_lshlrev_b32_e32 v136, 16, v186
	v_and_b32_e32 v137, 0xffff0000, v186
	v_lshlrev_b32_e32 v138, 16, v187
	v_and_b32_e32 v139, 0xffff0000, v187
	v_pk_mul_f32 v[228:229], v[130:131], v[228:229] op_sel_hi:[0,1]
	v_pk_fma_f32 v[228:229], v[20:21], v[228:229], v[136:137]
	v_pk_mul_f32 v[230:231], v[130:131], v[230:231] op_sel_hi:[0,1]
	v_pk_fma_f32 v[230:231], v[22:23], v[230:231], v[138:139]
	global_store_dwordx4 v[140:141], v[228:231], off offset:1024 nt
	v_lshlrev_b32_e32 v136, 16, v188
	v_and_b32_e32 v137, 0xffff0000, v188
	v_lshlrev_b32_e32 v138, 16, v189
	v_and_b32_e32 v139, 0xffff0000, v189
	v_pk_mul_f32 v[232:233], v[130:131], v[232:233] op_sel_hi:[0,1]
	v_pk_fma_f32 v[232:233], v[24:25], v[232:233], v[136:137]
	v_pk_mul_f32 v[234:235], v[130:131], v[234:235] op_sel_hi:[0,1]
	v_pk_fma_f32 v[234:235], v[26:27], v[234:235], v[138:139]
	global_store_dwordx4 v[140:141], v[232:235], off offset:2048 nt
	v_lshlrev_b32_e32 v136, 16, v190
	v_and_b32_e32 v137, 0xffff0000, v190
	v_lshlrev_b32_e32 v138, 16, v191
	v_and_b32_e32 v139, 0xffff0000, v191
	v_pk_mul_f32 v[236:237], v[130:131], v[236:237] op_sel_hi:[0,1]
	v_pk_fma_f32 v[236:237], v[28:29], v[236:237], v[136:137]
	v_pk_mul_f32 v[238:239], v[130:131], v[238:239] op_sel_hi:[0,1]
	v_pk_fma_f32 v[238:239], v[30:31], v[238:239], v[138:139]
	global_store_dwordx4 v[140:141], v[236:239], off offset:3072 nt
	v_lshl_add_u64 v[250:251], v[250:251], 0, s[12:13]
